# attention MODE0 steady loop: static s_setprio 1 for waves 4-7 (one per SIMD pair), reset at loop exit
# baseline (speedup 1.0000x reference)
.LBB0_796:
	v_lshlrev_b32_e32 v53, 1, v52
	v_lshlrev_b32_e32 v52, 4, v52
	v_and_b32_e32 v214, 32, v53
	v_and_b32_e32 v52, 0xc0, v52
	v_lshl_or_b32 v213, v209, 8, v52
	v_add_u32_e32 v52, 0, v214
	v_add3_u32 v219, v52, v211, v213
	v_max3_f32 v52, v36, v37, v20
	v_max3_f32 v53, v38, v39, v21
	s_and_b32 s0, s22, 0x3fffffc0
	v_max3_f32 v52, v52, v22, v23
	v_max3_f32 v53, v53, v42, v43
	s_lshl_b32 s0, s0, 2
	v_max3_f32 v52, v52, v40, v41
	v_max3_f32 v53, v53, v26, v27
	s_add_i32 s1, s64, 0x100
	v_max3_f32 v52, v52, v24, v25
	v_max3_f32 v53, v53, v46, v47
	s_add_i32 s53, s0, 0
	v_max3_f32 v52, v52, v44, v45
	v_max3_f32 v53, v53, v30, v31
	s_lshr_b32 s48, s1, 6
	v_max3_f32 v52, v52, v28, v29
	v_max3_f32 v53, v53, v50, v51
	s_mov_b64 s[22:23], 0x60000
	v_max3_f32 v52, v52, v48, v49
	v_max3_f32 v53, v53, v34, v35
	s_cmp_lg_u32 0, -1
	v_max3_f32 v52, v52, v32, v33
	s_mov_b64 s[10:11], 0x20000
	v_max_f32_e32 v52, v52, v53
	v_lshl_add_u64 v[190:191], v[84:85], 0, s[10:11]
	v_mov_b32_e32 v53, v52
	s_nop 1
	v_permlane32_swap_b32_e32 v52, v53
	v_max_f32_e32 v52, v52, v53
	s_mov_b32 s0, 1
	v_max_f32_e32 v52, v52, v228
	s_mov_b32 s24, 0
	v_add_f32_e32 v217, v3, v52
	v_sub_f32_e32 v53, v36, v52
	v_sub_f32_e32 v54, v37, v52
	v_sub_f32_e32 v55, v38, v52
	v_sub_f32_e32 v56, v39, v52
	v_sub_f32_e32 v57, v40, v52
	s_nop 0
	v_xor_b32_e32 v36, 0x80000000, v217
	v_sub_f32_e32 v58, v41, v52
	v_sub_f32_e32 v59, v42, v52
	v_sub_f32_e32 v60, v43, v52
	v_sub_f32_e32 v61, v44, v52
	v_sub_f32_e32 v62, v45, v52
	v_sub_f32_e32 v63, v46, v52
	v_sub_f32_e32 v64, v47, v52
	v_sub_f32_e32 v65, v48, v52
	v_sub_f32_e32 v66, v49, v52
	v_sub_f32_e32 v67, v50, v52
	v_sub_f32_e32 v83, v51, v52
	v_mov_b32_e32 v37, v36
	v_mov_b32_e32 v38, v36
	v_mov_b32_e32 v39, v36
	v_mov_b32_e32 v40, v36
	v_mov_b32_e32 v41, v36
	v_mov_b32_e32 v42, v36
	v_mov_b32_e32 v43, v36
	v_mov_b32_e32 v44, v36
	v_mov_b32_e32 v45, v36
	v_mov_b32_e32 v46, v36
	v_mov_b32_e32 v47, v36
	v_mov_b32_e32 v48, v36
	v_mov_b32_e32 v49, v36
	v_mov_b32_e32 v50, v36
	v_mov_b32_e32 v51, v36
	v_sub_f32_e32 v20, v20, v52
	v_sub_f32_e32 v21, v21, v52
	s_waitcnt vmcnt(0) lgkmcnt(0)
	s_barrier
	v_sub_f32_e32 v22, v22, v52
	v_sub_f32_e32 v23, v23, v52
	v_sub_f32_e32 v24, v24, v52
	v_sub_f32_e32 v25, v25, v52
	v_sub_f32_e32 v26, v26, v52
	v_sub_f32_e32 v27, v27, v52
	v_sub_f32_e32 v28, v28, v52
	v_sub_f32_e32 v29, v29, v52
	v_sub_f32_e32 v30, v30, v52
	v_sub_f32_e32 v31, v31, v52
	v_sub_f32_e32 v32, v32, v52
	v_sub_f32_e32 v33, v33, v52
	v_sub_f32_e32 v34, v34, v52
	v_sub_f32_e32 v35, v35, v52
	v_exp_f32_e32 v68, v53
	v_exp_f32_e32 v52, v20
	v_exp_f32_e32 v53, v21
	v_lshl_add_u64 v[20:21], v[188:189], 0, s[22:23]
	s_mov_b32 m0, s46
	s_nop 0
	global_load_lds_dwordx4 v[20:21], off
	s_cselect_b32 s1, 0, 0
	s_add_i32 s1, s1, s45
	s_add_i32 s1, s1, 0x8000
	s_mov_b32 m0, s1
	s_nop 0
	global_load_lds_dwordx4 v[190:191], off
	ds_read_b128 v[180:183], v218 offset:8192
	ds_read_b128 v[176:179], v218 offset:8704
	ds_read_b128 v[172:175], v218 offset:10240
	ds_read_b128 v[168:171], v218 offset:10752
	ds_read_b128 v[164:167], v218 offset:12288
	ds_read_b128 v[160:163], v218 offset:12800
	ds_read_b128 v[156:159], v218 offset:14336
	ds_read_b128 v[152:155], v218 offset:14848
	v_exp_f32_e32 v69, v54
	v_exp_f32_e32 v70, v55
	v_exp_f32_e32 v71, v56
	v_exp_f32_e32 v72, v57
	v_exp_f32_e32 v73, v58
	v_exp_f32_e32 v74, v59
	v_exp_f32_e32 v75, v60
	v_exp_f32_e32 v76, v61
	v_exp_f32_e32 v77, v62
	v_exp_f32_e32 v78, v63
	v_exp_f32_e32 v79, v64
	v_exp_f32_e32 v80, v65
	v_exp_f32_e32 v81, v66
	v_exp_f32_e32 v82, v67
	v_exp_f32_e32 v83, v83
	v_exp_f32_e32 v54, v22
	v_exp_f32_e32 v55, v23
	v_exp_f32_e32 v56, v24
	v_exp_f32_e32 v57, v25
	v_exp_f32_e32 v58, v26
	v_exp_f32_e32 v59, v27
	v_exp_f32_e32 v60, v28
	v_exp_f32_e32 v61, v29
	v_exp_f32_e32 v62, v30
	v_exp_f32_e32 v63, v31
	v_exp_f32_e32 v64, v32
	v_exp_f32_e32 v65, v33
	v_exp_f32_e32 v66, v34
	v_exp_f32_e32 v67, v35
	s_waitcnt vmcnt(2) lgkmcnt(0)
	s_barrier
	s_andn2_b64 vcc, exec, s[4:5]
	v_cmp_gt_u32_e64 s[4:5], 32, v1
	s_cbranch_vccnz .LBB0_812
	v_lshlrev_b32_e32 v20, 4, v209
	s_mov_b64 s[10:11], 0xa0000
	v_add_u32_e32 v203, s53, v20
	v_mov_b64_e32 v[34:35], v[18:19]
	s_add_i32 s1, s48, -5
	v_lshl_add_u32 v202, v208, 2, s53
	v_lshl_add_u64 v[192:193], v[84:85], 0, s[22:23]
	v_lshl_add_u64 v[194:195], v[188:189], 0, s[10:11]
	s_movk_i32 s24, 0x4000
	s_movk_i32 s25, 0x2000
	s_mov_b32 s10, 0
	v_mov_b32_e32 v220, 0
	v_mov_b64_e32 v[32:33], v[16:17]
	v_mov_b64_e32 v[30:31], v[14:15]
	v_mov_b64_e32 v[28:29], v[12:13]
	v_mov_b64_e32 v[26:27], v[10:11]
	v_mov_b64_e32 v[24:25], v[8:9]
	v_mov_b64_e32 v[22:23], v[6:7]
	v_mov_b64_e32 v[20:21], v[4:5]
	s_mov_b64 s[98:99], exec
	v_and_b32_e32 v224, 0xffff0000, v36
	v_sub_f32_e32 v225, v224, v36
	v_exp_f32_e32 v225, v225
	v_bfe_i32 v196, v132, 0, 1
	v_mov_b32_e32 v250, 0
	v_mov_b32_e32 v251, 0
	v_mov_b32_e32 v252, 0
	v_mov_b32_e32 v253, 0
	v_mov_b32_e32 v247, 0
	v_mov_b32_e32 v248, 0
	v_mov_b32_e32 v249, 0
	v_mov_b32_e32 v222, 0
	v_mov_b32_e32 v223, 0
	s_mov_b32 exec_hi, 0
	v_mov_b32_e32 v250, 0x3f80
	v_mov_b32_e32 v223, 0xf180
	v_lshrrev_b32_e32 v222, 16, v224
	s_mov_b64 exec, s[98:99]
	v_readfirstlane_b32 s98, v192
	v_readfirstlane_b32 s99, v193
	s_sub_u32 s98, s98, 0x1000000
	s_subb_u32 s99, s99, 0
	v_subrev_u32_e32 v199, s98, v192
	v_subrev_u32_e32 v198, s98, v194
	v_add_u32_e32 v203, 0xfffe0000, v199
	v_add_u32_e32 v202, 0xfffe0000, v198
	v_and_b32_e32 v224, v225, v196
	v_mul_f32_e32 v4, v225, v4
	v_mul_f32_e32 v5, v225, v5
	v_mul_f32_e32 v6, v225, v6
	v_mul_f32_e32 v7, v225, v7
	v_mul_f32_e32 v8, v225, v8
	v_mul_f32_e32 v9, v225, v9
	v_mul_f32_e32 v10, v225, v10
	v_mul_f32_e32 v11, v225, v11
	v_mul_f32_e32 v12, v225, v12
	v_mul_f32_e32 v13, v225, v13
	v_mul_f32_e32 v14, v225, v14
	v_mul_f32_e32 v15, v225, v15
	v_mul_f32_e32 v16, v225, v16
	v_mul_f32_e32 v17, v225, v17
	v_mul_f32_e32 v18, v225, v18
	v_mul_f32_e32 v19, v225, v19
	v_mul_f32_e32 v20, v225, v20
	v_mul_f32_e32 v21, v225, v21
	v_mul_f32_e32 v22, v225, v22
	v_mul_f32_e32 v23, v225, v23
	v_mul_f32_e32 v24, v225, v24
	v_mul_f32_e32 v25, v225, v25
	v_mul_f32_e32 v26, v225, v26
	v_mul_f32_e32 v27, v225, v27
	v_mul_f32_e32 v28, v225, v28
	v_mul_f32_e32 v29, v225, v29
	v_mul_f32_e32 v30, v225, v30
	v_mul_f32_e32 v31, v225, v31
	v_mul_f32_e32 v32, v225, v32
	v_mul_f32_e32 v33, v225, v33
	v_mul_f32_e32 v34, v225, v34
	v_mul_f32_e32 v35, v225, v35
	v_mul_f32_e32 v52, v224, v52
	v_mul_f32_e32 v53, v224, v53
	v_mul_f32_e32 v54, v224, v54
	v_mul_f32_e32 v55, v224, v55
	v_mul_f32_e32 v56, v224, v56
	v_mul_f32_e32 v57, v224, v57
	v_mul_f32_e32 v58, v224, v58
	v_mul_f32_e32 v59, v224, v59
	v_mul_f32_e32 v60, v224, v60
	v_mul_f32_e32 v61, v224, v61
	v_mul_f32_e32 v62, v224, v62
	v_mul_f32_e32 v63, v224, v63
	v_mul_f32_e32 v64, v224, v64
	v_mul_f32_e32 v65, v224, v65
	v_mul_f32_e32 v66, v224, v66
	v_mul_f32_e32 v67, v224, v67
	v_mul_f32_e32 v68, v224, v68
	v_mul_f32_e32 v69, v224, v69
	v_mul_f32_e32 v70, v224, v70
	v_mul_f32_e32 v71, v224, v71
	v_mul_f32_e32 v72, v224, v72
	v_mul_f32_e32 v73, v224, v73
	v_mul_f32_e32 v74, v224, v74
	v_mul_f32_e32 v75, v224, v75
	v_mul_f32_e32 v76, v224, v76
	v_mul_f32_e32 v77, v224, v77
	v_mul_f32_e32 v78, v224, v78
	v_mul_f32_e32 v79, v224, v79
	v_mul_f32_e32 v80, v224, v80
	v_mul_f32_e32 v81, v224, v81
	v_mul_f32_e32 v82, v224, v82
	v_mul_f32_e32 v83, v224, v83
	v_mul_f32_e32 v220, v225, v220
	v_bfe_i32 v196, v132, 1, 1
	v_bfi_b32 v246, v196, v222, v223
	s_mov_b32 s101, 2
	v_readfirstlane_b32 s100, v0
	s_cmp_lt_u32 s100, 0x100
	s_cbranch_scc1 .Lattn0_noprio
	s_setprio 1
.Lattn0_noprio:
	s_nop 1
	v_mfma_f32_32x32x16_bf16 v[36:51], v[250:253], v[246:249], 0
	s_branch .LBB0_798

.Lattn0_exit:
	s_setprio 0
	v_mov_b32_e32 v193, s99
	v_mov_b32_e32 v195, s99
	v_add_co_u32_e32 v192, vcc, s98, v199
	v_addc_co_u32_e32 v193, vcc, 0, v193, vcc
	v_add_co_u32_e32 v194, vcc, s98, v198
	v_addc_co_u32_e32 v195, vcc, 0, v195, vcc
	s_sub_i32 s100, s101, 2
	v_mov_b32_e32 v246, v222
	v_alignbit_b32 v132, v133, v132, s100
	v_alignbit_b32 v133, v134, v133, s100
	v_alignbit_b32 v134, v135, v134, s100
	v_lshrrev_b32_e32 v135, s100, v135
	v_mfma_f32_32x32x16_bf16 v[36:51], v[250:253], v[246:249], 0
	s_nop 7
	s_nop 3
	s_waitcnt vmcnt(2) lgkmcnt(0)
	s_barrier
	s_branch .LBB0_813
